# v10 + P12 small_gemm K-loop: uniform 4-chunk-deep load pipeline (24 loads in flight) instead of one serialized round trip per chunk
# baseline (speedup 1.0000x reference)
.LBB0_1461:
	s_and_b32 s0, s4, 0xffffffc0
	v_or_b32_e32 v0, s0, v40
	v_mad_i64_i32 v[12:13], s[8:9], v0, s6, v[34:35]
	v_add_co_u32_e32 v16, vcc, 0x16000, v12
	s_and_b32 s7, s3, 0x3e0
	s_nop 0
	v_addc_co_u32_e32 v17, vcc, 0, v13, vcc
	v_or_b32_e32 v1, s7, v40
	v_add_co_u32_e32 v20, vcc, 0x2c000, v12
	v_mul_u32_u24_e32 v0, 0xb00, v1
	s_nop 0
	v_addc_co_u32_e32 v21, vcc, 0, v13, vcc
	v_lshlrev_b32_e32 v32, 1, v0
	v_add_co_u32_e32 v218, vcc, 0x42000, v12
	v_lshl_add_u64 v[18:19], v[36:37], 0, v[32:33]
	s_nop 0
	v_addc_co_u32_e32 v219, vcc, 0, v13, vcc
	v_add_co_u32_e32 v242, vcc, 0x16000, v18
	s_nop 1
	v_addc_co_u32_e32 v243, vcc, 0, v19, vcc
	v_or_b32_e32 v32, s0, v41
	s_lshl_b32 s0, s7, 1
	s_add_i32 s2, s2, s96
	s_add_i32 s3, s3, s86
	s_add_i32 s4, s4, s5
	s_cmpk_lt_i32 s2, 0x100
	s_waitcnt vmcnt(0)
	v_mov_b64_e32 v[198:199], v[12:13]
	v_mov_b64_e32 v[200:201], v[16:17]
	v_mov_b64_e32 v[202:203], v[20:21]
	v_mov_b64_e32 v[204:205], v[18:19]
	global_load_dwordx4 v[54:57], v[198:199], off
	global_load_dwordx4 v[58:61], v[200:201], off
	global_load_dwordx4 v[62:65], v[202:203], off
	global_load_dwordx4 v[66:69], v[218:219], off
	global_load_dwordx4 v[70:73], v[204:205], off
	global_load_dwordx4 v[74:77], v[242:243], off
	global_load_dwordx4 v[78:81], v[198:199], off offset:64
	global_load_dwordx4 v[82:85], v[200:201], off offset:64
	global_load_dwordx4 v[86:89], v[202:203], off offset:64
	global_load_dwordx4 v[90:93], v[218:219], off offset:64
	global_load_dwordx4 v[94:97], v[204:205], off offset:64
	global_load_dwordx4 v[98:101], v[242:243], off offset:64
	global_load_dwordx4 v[102:105], v[198:199], off offset:128
	global_load_dwordx4 v[106:109], v[200:201], off offset:128
	global_load_dwordx4 v[110:113], v[202:203], off offset:128
	global_load_dwordx4 v[114:117], v[218:219], off offset:128
	global_load_dwordx4 v[118:121], v[204:205], off offset:128
	global_load_dwordx4 v[122:125], v[242:243], off offset:128
	global_load_dwordx4 v[126:129], v[198:199], off offset:192
	global_load_dwordx4 v[130:133], v[200:201], off offset:192
	global_load_dwordx4 v[134:137], v[202:203], off offset:192
	global_load_dwordx4 v[138:141], v[218:219], off offset:192
	global_load_dwordx4 v[142:145], v[204:205], off offset:192
	global_load_dwordx4 v[146:149], v[242:243], off offset:192
	s_waitcnt vmcnt(18)
	ds_write_b128 v46, v[54:57]
	ds_write_b128 v46, v[58:61] offset:1280
	ds_write_b128 v46, v[62:65] offset:2560
	ds_write_b128 v46, v[66:69] offset:3840
	ds_write_b128 v46, v[70:73] offset:5120
	ds_write_b128 v46, v[74:77] offset:6400
	ds_read_b128 v[174:177], v47
	ds_read_b128 v[178:181], v47 offset:5120
	ds_read_b128 v[182:185], v47 offset:32
	ds_read_b128 v[186:189], v47 offset:5152
	ds_read_b128 v[190:193], v47 offset:2560
	ds_read_b128 v[194:197], v47 offset:2592
	global_load_dwordx4 v[150:153], v[198:199], off offset:256
	global_load_dwordx4 v[154:157], v[200:201], off offset:256
	global_load_dwordx4 v[158:161], v[202:203], off offset:256
	global_load_dwordx4 v[162:165], v[218:219], off offset:256
	global_load_dwordx4 v[166:169], v[204:205], off offset:256
	global_load_dwordx4 v[170:173], v[242:243], off offset:256
	s_waitcnt vmcnt(18)
	ds_write_b128 v46, v[78:81]
	ds_write_b128 v46, v[82:85] offset:1280
	ds_write_b128 v46, v[86:89] offset:2560
	ds_write_b128 v46, v[90:93] offset:3840
	ds_write_b128 v46, v[94:97] offset:5120
	ds_write_b128 v46, v[98:101] offset:6400
	ds_read_b128 v[206:209], v47
	ds_read_b128 v[210:213], v47 offset:5120
	ds_read_b128 v[214:217], v47 offset:32
	ds_read_b128 v[222:225], v47 offset:5152
	ds_read_b128 v[226:229], v47 offset:2560
	ds_read_b128 v[230:233], v47 offset:2592
	global_load_dwordx4 v[54:57], v[198:199], off offset:320
	global_load_dwordx4 v[58:61], v[200:201], off offset:320
	global_load_dwordx4 v[62:65], v[202:203], off offset:320
	global_load_dwordx4 v[66:69], v[218:219], off offset:320
	global_load_dwordx4 v[70:73], v[204:205], off offset:320
	global_load_dwordx4 v[74:77], v[242:243], off offset:320
	s_waitcnt lgkmcnt(12)
	v_mfma_f32_32x32x16_bf16 v[0:15], v[174:177], v[178:181], 0
	v_mfma_f32_32x32x16_bf16 v[16:31], v[190:193], v[178:181], 0
	v_mfma_f32_32x32x16_bf16 v[0:15], v[182:185], v[186:189], v[0:15]
	v_mfma_f32_32x32x16_bf16 v[16:31], v[194:197], v[186:189], v[16:31]
	s_waitcnt vmcnt(18)
	ds_write_b128 v46, v[102:105]
	ds_write_b128 v46, v[106:109] offset:1280
	ds_write_b128 v46, v[110:113] offset:2560
	ds_write_b128 v46, v[114:117] offset:3840
	ds_write_b128 v46, v[118:121] offset:5120
	ds_write_b128 v46, v[122:125] offset:6400
	ds_read_b128 v[174:177], v47
	ds_read_b128 v[178:181], v47 offset:5120
	ds_read_b128 v[182:185], v47 offset:32
	ds_read_b128 v[186:189], v47 offset:5152
	ds_read_b128 v[190:193], v47 offset:2560
	ds_read_b128 v[194:197], v47 offset:2592
	global_load_dwordx4 v[78:81], v[198:199], off offset:384
	global_load_dwordx4 v[82:85], v[200:201], off offset:384
	global_load_dwordx4 v[86:89], v[202:203], off offset:384
	global_load_dwordx4 v[90:93], v[218:219], off offset:384
	global_load_dwordx4 v[94:97], v[204:205], off offset:384
	global_load_dwordx4 v[98:101], v[242:243], off offset:384
	s_waitcnt lgkmcnt(12)
	v_mfma_f32_32x32x16_bf16 v[0:15], v[206:209], v[210:213], v[0:15]
	v_mfma_f32_32x32x16_bf16 v[16:31], v[226:229], v[210:213], v[16:31]
	v_mfma_f32_32x32x16_bf16 v[0:15], v[214:217], v[222:225], v[0:15]
	v_mfma_f32_32x32x16_bf16 v[16:31], v[230:233], v[222:225], v[16:31]
	s_waitcnt vmcnt(18)
	ds_write_b128 v46, v[126:129]
	ds_write_b128 v46, v[130:133] offset:1280
	ds_write_b128 v46, v[134:137] offset:2560
	ds_write_b128 v46, v[138:141] offset:3840
	ds_write_b128 v46, v[142:145] offset:5120
	ds_write_b128 v46, v[146:149] offset:6400
	ds_read_b128 v[206:209], v47
	ds_read_b128 v[210:213], v47 offset:5120
	ds_read_b128 v[214:217], v47 offset:32
	ds_read_b128 v[222:225], v47 offset:5152
	ds_read_b128 v[226:229], v47 offset:2560
	ds_read_b128 v[230:233], v47 offset:2592
	global_load_dwordx4 v[102:105], v[198:199], off offset:448
	global_load_dwordx4 v[106:109], v[200:201], off offset:448
	global_load_dwordx4 v[110:113], v[202:203], off offset:448
	global_load_dwordx4 v[114:117], v[218:219], off offset:448
	global_load_dwordx4 v[118:121], v[204:205], off offset:448
	global_load_dwordx4 v[122:125], v[242:243], off offset:448
	s_waitcnt lgkmcnt(12)
	v_mfma_f32_32x32x16_bf16 v[0:15], v[174:177], v[178:181], v[0:15]
	v_mfma_f32_32x32x16_bf16 v[16:31], v[190:193], v[178:181], v[16:31]
	v_mfma_f32_32x32x16_bf16 v[0:15], v[182:185], v[186:189], v[0:15]
	v_mfma_f32_32x32x16_bf16 v[16:31], v[194:197], v[186:189], v[16:31]
	s_waitcnt vmcnt(18)
	ds_write_b128 v46, v[150:153]
	ds_write_b128 v46, v[154:157] offset:1280
	ds_write_b128 v46, v[158:161] offset:2560
	ds_write_b128 v46, v[162:165] offset:3840
	ds_write_b128 v46, v[166:169] offset:5120
	ds_write_b128 v46, v[170:173] offset:6400
	ds_read_b128 v[174:177], v47
	ds_read_b128 v[178:181], v47 offset:5120
	ds_read_b128 v[182:185], v47 offset:32
	ds_read_b128 v[186:189], v47 offset:5152
	ds_read_b128 v[190:193], v47 offset:2560
	ds_read_b128 v[194:197], v47 offset:2592
	global_load_dwordx4 v[126:129], v[198:199], off offset:512
	global_load_dwordx4 v[130:133], v[200:201], off offset:512
	global_load_dwordx4 v[134:137], v[202:203], off offset:512
	global_load_dwordx4 v[138:141], v[218:219], off offset:512
	global_load_dwordx4 v[142:145], v[204:205], off offset:512
	global_load_dwordx4 v[146:149], v[242:243], off offset:512
	s_waitcnt lgkmcnt(12)
	v_mfma_f32_32x32x16_bf16 v[0:15], v[206:209], v[210:213], v[0:15]
	v_mfma_f32_32x32x16_bf16 v[16:31], v[226:229], v[210:213], v[16:31]
	v_mfma_f32_32x32x16_bf16 v[0:15], v[214:217], v[222:225], v[0:15]
	v_mfma_f32_32x32x16_bf16 v[16:31], v[230:233], v[222:225], v[16:31]
	s_waitcnt vmcnt(18)
	ds_write_b128 v46, v[54:57]
	ds_write_b128 v46, v[58:61] offset:1280
	ds_write_b128 v46, v[62:65] offset:2560
	ds_write_b128 v46, v[66:69] offset:3840
	ds_write_b128 v46, v[70:73] offset:5120
	ds_write_b128 v46, v[74:77] offset:6400
	ds_read_b128 v[206:209], v47
	ds_read_b128 v[210:213], v47 offset:5120
	ds_read_b128 v[214:217], v47 offset:32
	ds_read_b128 v[222:225], v47 offset:5152
	ds_read_b128 v[226:229], v47 offset:2560
	ds_read_b128 v[230:233], v47 offset:2592
	global_load_dwordx4 v[150:153], v[198:199], off offset:576
	global_load_dwordx4 v[154:157], v[200:201], off offset:576
	global_load_dwordx4 v[158:161], v[202:203], off offset:576
	global_load_dwordx4 v[162:165], v[218:219], off offset:576
	global_load_dwordx4 v[166:169], v[204:205], off offset:576
	global_load_dwordx4 v[170:173], v[242:243], off offset:576
	s_waitcnt lgkmcnt(12)
	v_mfma_f32_32x32x16_bf16 v[0:15], v[174:177], v[178:181], v[0:15]
	v_mfma_f32_32x32x16_bf16 v[16:31], v[190:193], v[178:181], v[16:31]
	v_mfma_f32_32x32x16_bf16 v[0:15], v[182:185], v[186:189], v[0:15]
	v_mfma_f32_32x32x16_bf16 v[16:31], v[194:197], v[186:189], v[16:31]
	s_waitcnt vmcnt(18)
	ds_write_b128 v46, v[78:81]
	ds_write_b128 v46, v[82:85] offset:1280
	ds_write_b128 v46, v[86:89] offset:2560
	ds_write_b128 v46, v[90:93] offset:3840
	ds_write_b128 v46, v[94:97] offset:5120
	ds_write_b128 v46, v[98:101] offset:6400
	ds_read_b128 v[174:177], v47
	ds_read_b128 v[178:181], v47 offset:5120
	ds_read_b128 v[182:185], v47 offset:32
	ds_read_b128 v[186:189], v47 offset:5152
	ds_read_b128 v[190:193], v47 offset:2560
	ds_read_b128 v[194:197], v47 offset:2592
	global_load_dwordx4 v[54:57], v[198:199], off offset:640
	global_load_dwordx4 v[58:61], v[200:201], off offset:640
	global_load_dwordx4 v[62:65], v[202:203], off offset:640
	global_load_dwordx4 v[66:69], v[218:219], off offset:640
	global_load_dwordx4 v[70:73], v[204:205], off offset:640
	global_load_dwordx4 v[74:77], v[242:243], off offset:640
	s_waitcnt lgkmcnt(12)
	v_mfma_f32_32x32x16_bf16 v[0:15], v[206:209], v[210:213], v[0:15]
	v_mfma_f32_32x32x16_bf16 v[16:31], v[226:229], v[210:213], v[16:31]
	v_mfma_f32_32x32x16_bf16 v[0:15], v[214:217], v[222:225], v[0:15]
	v_mfma_f32_32x32x16_bf16 v[16:31], v[230:233], v[222:225], v[16:31]
	s_waitcnt vmcnt(18)
	ds_write_b128 v46, v[102:105]
	ds_write_b128 v46, v[106:109] offset:1280
	ds_write_b128 v46, v[110:113] offset:2560
	ds_write_b128 v46, v[114:117] offset:3840
	ds_write_b128 v46, v[118:121] offset:5120
	ds_write_b128 v46, v[122:125] offset:6400
	ds_read_b128 v[206:209], v47
	ds_read_b128 v[210:213], v47 offset:5120
	ds_read_b128 v[214:217], v47 offset:32
	ds_read_b128 v[222:225], v47 offset:5152
	ds_read_b128 v[226:229], v47 offset:2560
	ds_read_b128 v[230:233], v47 offset:2592
	s_waitcnt lgkmcnt(12)
	v_mfma_f32_32x32x16_bf16 v[0:15], v[174:177], v[178:181], v[0:15]
	v_mfma_f32_32x32x16_bf16 v[16:31], v[190:193], v[178:181], v[16:31]
	v_mfma_f32_32x32x16_bf16 v[0:15], v[182:185], v[186:189], v[0:15]
	v_mfma_f32_32x32x16_bf16 v[16:31], v[194:197], v[186:189], v[16:31]
	s_waitcnt vmcnt(12)
	ds_write_b128 v46, v[126:129]
	ds_write_b128 v46, v[130:133] offset:1280
	ds_write_b128 v46, v[134:137] offset:2560
	ds_write_b128 v46, v[138:141] offset:3840
	ds_write_b128 v46, v[142:145] offset:5120
	ds_write_b128 v46, v[146:149] offset:6400
	ds_read_b128 v[174:177], v47
	ds_read_b128 v[178:181], v47 offset:5120
	ds_read_b128 v[182:185], v47 offset:32
	ds_read_b128 v[186:189], v47 offset:5152
	ds_read_b128 v[190:193], v47 offset:2560
	ds_read_b128 v[194:197], v47 offset:2592
	s_waitcnt lgkmcnt(12)
	v_mfma_f32_32x32x16_bf16 v[0:15], v[206:209], v[210:213], v[0:15]
	v_mfma_f32_32x32x16_bf16 v[16:31], v[226:229], v[210:213], v[16:31]
	v_mfma_f32_32x32x16_bf16 v[0:15], v[214:217], v[222:225], v[0:15]
	v_mfma_f32_32x32x16_bf16 v[16:31], v[230:233], v[222:225], v[16:31]
	s_waitcnt vmcnt(6)
	ds_write_b128 v46, v[150:153]
	ds_write_b128 v46, v[154:157] offset:1280
	ds_write_b128 v46, v[158:161] offset:2560
	ds_write_b128 v46, v[162:165] offset:3840
	ds_write_b128 v46, v[166:169] offset:5120
	ds_write_b128 v46, v[170:173] offset:6400
	ds_read_b128 v[206:209], v47
	ds_read_b128 v[210:213], v47 offset:5120
	ds_read_b128 v[214:217], v47 offset:32
	ds_read_b128 v[222:225], v47 offset:5152
	ds_read_b128 v[226:229], v47 offset:2560
	ds_read_b128 v[230:233], v47 offset:2592
	s_waitcnt lgkmcnt(12)
	v_mfma_f32_32x32x16_bf16 v[0:15], v[174:177], v[178:181], v[0:15]
	v_mfma_f32_32x32x16_bf16 v[16:31], v[190:193], v[178:181], v[16:31]
	v_mfma_f32_32x32x16_bf16 v[0:15], v[182:185], v[186:189], v[0:15]
	v_mfma_f32_32x32x16_bf16 v[16:31], v[194:197], v[186:189], v[16:31]
	s_waitcnt vmcnt(0)
	ds_write_b128 v46, v[54:57]
	ds_write_b128 v46, v[58:61] offset:1280
	ds_write_b128 v46, v[62:65] offset:2560
	ds_write_b128 v46, v[66:69] offset:3840
	ds_write_b128 v46, v[70:73] offset:5120
	ds_write_b128 v46, v[74:77] offset:6400
	ds_read_b128 v[174:177], v47
	ds_read_b128 v[178:181], v47 offset:5120
	ds_read_b128 v[182:185], v47 offset:32
	ds_read_b128 v[186:189], v47 offset:5152
	ds_read_b128 v[190:193], v47 offset:2560
	ds_read_b128 v[194:197], v47 offset:2592
	s_waitcnt lgkmcnt(12)
	v_mfma_f32_32x32x16_bf16 v[0:15], v[206:209], v[210:213], v[0:15]
	v_mfma_f32_32x32x16_bf16 v[16:31], v[226:229], v[210:213], v[16:31]
	v_mfma_f32_32x32x16_bf16 v[0:15], v[214:217], v[222:225], v[0:15]
	v_mfma_f32_32x32x16_bf16 v[16:31], v[230:233], v[222:225], v[16:31]
	v_add_u32_e32 v80, v32, v42
	v_ashrrev_i32_e32 v81, 31, v80
	v_lshl_add_u64 v[78:79], v[38:39], 0, s[0:1]
	v_add_u32_e32 v82, v32, v43
	v_add_u32_e32 v84, v32, v44
	v_ashrrev_i32_e32 v83, 31, v82
	v_ashrrev_i32_e32 v85, 31, v84
	s_waitcnt lgkmcnt(0)
	v_mfma_f32_32x32x16_bf16 v[0:15], v[174:177], v[178:181], v[0:15]
	v_mfma_f32_32x32x16_bf16 v[16:31], v[190:193], v[178:181], v[16:31]
	v_add_u32_e32 v54, v32, v45
	v_ashrrev_i32_e32 v55, 31, v54
	v_lshlrev_b64 v[56:57], 11, v[80:81]
	v_lshlrev_b64 v[58:59], 11, v[82:83]
	v_lshlrev_b64 v[60:61], 11, v[84:85]
	v_lshlrev_b64 v[54:55], 11, v[54:55]
	v_lshl_add_u64 v[56:57], v[78:79], 0, v[56:57]
	v_mfma_f32_32x32x16_bf16 v[0:15], v[182:185], v[186:189], v[0:15]
	v_lshl_add_u64 v[58:59], v[78:79], 0, v[58:59]
	v_lshl_add_u64 v[60:61], v[78:79], 0, v[60:61]
	v_lshl_add_u64 v[54:55], v[78:79], 0, v[54:55]
	v_mfma_f32_32x32x16_bf16 v[16:31], v[194:197], v[186:189], v[16:31]
	s_nop 6
	ds_write2st64_b32 v48, v0, v1 offset1:1
	s_nop 3
	ds_write2st64_b32 v48, v16, v17 offset0:16 offset1:17
	ds_write2st64_b32 v48, v2, v3 offset0:2 offset1:3
	ds_write2st64_b32 v48, v18, v19 offset0:18 offset1:19
	ds_write2st64_b32 v48, v4, v5 offset0:4 offset1:5
	ds_write2st64_b32 v48, v20, v21 offset0:20 offset1:21
	ds_write2st64_b32 v48, v6, v7 offset0:6 offset1:7
	ds_write2st64_b32 v48, v22, v23 offset0:22 offset1:23
	ds_write2st64_b32 v48, v8, v9 offset0:8 offset1:9
	ds_write2st64_b32 v48, v24, v25 offset0:24 offset1:25
	ds_write2st64_b32 v48, v10, v11 offset0:10 offset1:11
	ds_write2st64_b32 v48, v26, v27 offset0:26 offset1:27
	ds_write2st64_b32 v48, v12, v13 offset0:12 offset1:13
	ds_write2st64_b32 v48, v28, v29 offset0:28 offset1:29
	ds_write2st64_b32 v48, v14, v15 offset0:14 offset1:15
	ds_write2st64_b32 v48, v30, v31 offset0:30 offset1:31
	s_waitcnt lgkmcnt(0)
	s_barrier
	ds_read2st64_b32 v[0:1], v49 offset1:32
	ds_read2st64_b32 v[2:3], v49 offset0:64 offset1:96
	ds_read2st64_b32 v[4:5], v49 offset0:128 offset1:160
	ds_read2st64_b32 v[6:7], v49 offset0:192 offset1:224
	ds_read2st64_b32 v[8:9], v50 offset1:32
	ds_read2st64_b32 v[10:11], v50 offset0:64 offset1:96
	ds_read2st64_b32 v[12:13], v50 offset0:128 offset1:160
	ds_read2st64_b32 v[14:15], v50 offset0:192 offset1:224
	ds_read2st64_b32 v[16:17], v51 offset1:32
	ds_read2st64_b32 v[18:19], v51 offset0:64 offset1:96
	ds_read2st64_b32 v[20:21], v51 offset0:128 offset1:160
	ds_read2st64_b32 v[22:23], v51 offset0:192 offset1:224
	ds_read2st64_b32 v[24:25], v52 offset1:32
	ds_read2st64_b32 v[26:27], v52 offset0:64 offset1:96
	ds_read2st64_b32 v[28:29], v52 offset0:128 offset1:160
	ds_read2st64_b32 v[30:31], v52 offset0:192 offset1:224
	s_waitcnt lgkmcnt(14)
	v_add_f32_e32 v0, 0, v0
	s_waitcnt lgkmcnt(11)
	v_add_f32_e32 v8, 0, v8
	s_waitcnt lgkmcnt(7)
	v_add_f32_e32 v16, 0, v16
	s_waitcnt lgkmcnt(3)
	v_add_f32_e32 v24, 0, v24
	v_add_f32_e32 v0, v0, v1
	v_add_f32_e32 v1, v8, v9
	v_add_f32_e32 v8, v16, v17
	v_add_f32_e32 v9, v24, v25
	v_add_f32_e32 v0, v0, v2
	v_add_f32_e32 v1, v1, v10
	v_add_f32_e32 v2, v8, v18
	s_waitcnt lgkmcnt(2)
	v_add_f32_e32 v8, v9, v26
	v_add_f32_e32 v0, v0, v3
	v_add_f32_e32 v1, v1, v11
	v_add_f32_e32 v2, v2, v19
	v_add_f32_e32 v3, v8, v27
	v_add_f32_e32 v0, v0, v4
	v_add_f32_e32 v1, v1, v12
	v_add_f32_e32 v2, v2, v20
	s_waitcnt lgkmcnt(1)
	v_add_f32_e32 v3, v3, v28
	v_add_f32_e32 v0, v0, v5
	v_add_f32_e32 v1, v1, v13
	v_add_f32_e32 v2, v2, v21
	v_add_f32_e32 v3, v3, v29
	v_add_f32_e32 v0, v0, v6
	v_add_f32_e32 v1, v1, v14
	v_add_f32_e32 v2, v2, v22
	s_waitcnt lgkmcnt(0)
	v_add_f32_e32 v3, v3, v30
	v_add_f32_e32 v0, v0, v7
	v_add_f32_e32 v1, v1, v15
	v_add_f32_e32 v2, v2, v23
	v_add_f32_e32 v3, v3, v31
	v_cvt_pk_bf16_f32 v0, v0, s0
	v_cvt_pk_bf16_f32 v1, v1, s0
	v_cvt_pk_bf16_f32 v2, v2, s0
	v_cvt_pk_bf16_f32 v3, v3, s0
	global_store_short v[56:57], v0, off
	global_store_short v[58:59], v1, off
	global_store_short v[60:61], v2, off
	global_store_short v[54:55], v3, off
	s_barrier
	s_cbranch_scc1 .LBB0_1461
